# p3_compress: A/w1t loads, BIAS1 partial-sum loads and w2 loads issued in batches instead of one wait per load (same MFMA/FMA order)
# speedup vs baseline: 1.0416x; 1.0287x over previous
.LBB0_372:
	s_lshl_b32 s3, s7, 4
	s_and_b32 s8, s3, 0x7f0
	v_or_b32_e32 v23, s8, v17
	v_min_u32_e32 v23, 0x7f7, v23
	v_lshrrev_b32_e32 v25, 1, v23
	v_mul_u32_u24_e32 v26, 0x405, v25
	v_lshrrev_b32_e32 v26, 18, v26
	v_mul_lo_u16_e32 v26, 0xff, v26
	v_sub_u16_e32 v25, v25, v26
	v_mul_u32_u24_e32 v26, 0x809, v23
	v_lshrrev_b32_e32 v26, 16, v26
	v_lshlrev_b16_e32 v26, 8, v26
	v_lshlrev_b16_e32 v25, 4, v25
	s_movk_i32 s3, 0x7000
	v_bitop3_b16 v25, v25, v26, s3 bitop3:0xf8
	v_and_b32_e32 v25, 0xffff, v25
	v_mov_b64_e32 v[26:27], s[84:85]
	v_mad_u64_u32 v[26:27], s[4:5], v25, s76, v[26:27]
	s_and_b32 s4, s7, 0xffffff80
	s_ashr_i32 s5, s4, 31
	v_lshlrev_b32_e32 v23, 7, v23
	v_lshl_add_u64 v[26:27], s[4:5], 1, v[26:27]
	v_and_b32_e32 v64, 0x80, v23
	v_lshl_add_u64 v[26:27], v[26:27], 0, v[64:65]
	s_mov_b64 s[4:5], 0x7e00200
	v_lshl_add_u64 v[34:35], v[26:27], 0, s[4:5]
	s_ashr_i32 s38, s7, 7
	v_lshl_add_u64 v[28:29], v[34:35], 0, s[46:47]
	v_mov_b32_e32 v23, v65
	s_add_i32 s40, s38, s16
	v_lshl_add_u64 v[70:71], v[28:29], 0, v[22:23]
	s_ashr_i32 s41, s40, 31
	s_lshl_b64 s[4:5], s[40:41], 18
	v_mov_b32_e32 v27, s5
	v_or_b32_e32 v26, s4, v16
	v_or_b32_e32 v30, 0x10000, v26
	v_mov_b32_e32 v31, s5
	v_or_b32_e32 v28, 0x20000, v26
	v_mov_b32_e32 v29, s5
	v_or_b32_e32 v72, 0x30000, v26
	v_mov_b32_e32 v73, s5
	s_ashr_i32 s39, s38, 31
	v_lshl_add_u64 v[32:33], v[0:1], 0, v[26:27]
	v_lshl_add_u64 v[74:75], v[34:35], 0, s[58:59]
	v_lshl_add_u64 v[74:75], v[74:75], 0, v[22:23]
	v_lshl_add_u64 v[66:67], v[34:35], 0, s[18:19]
	v_lshl_add_u64 v[66:67], v[66:67], 0, v[22:23]
	v_lshl_add_u64 v[34:35], v[34:35], 0, s[20:21]
	v_lshl_add_u64 v[34:35], v[34:35], 0, v[22:23]
	v_readlane_b32 s4, v250, 13
	v_readlane_b32 s5, v250, 14
	global_load_dwordx4 v[80:83], v[70:71], off
	global_load_dwordx4 v[84:87], v[32:33], off
	v_lshl_add_u64 v[200:201], v[0:1], 0, v[30:31]
	global_load_dwordx4 v[88:91], v[200:201], off
	v_lshl_add_u64 v[202:203], v[0:1], 0, v[28:29]
	global_load_dwordx4 v[92:95], v[202:203], off
	v_lshl_add_u64 v[204:205], v[0:1], 0, v[72:73]
	global_load_dwordx4 v[96:99], v[204:205], off
	global_load_dwordx4 v[100:103], v[70:71], off offset:64
	global_load_dwordx4 v[104:107], v[32:33], off offset:64
	v_lshl_add_u64 v[200:201], v[2:3], 0, v[30:31]
	global_load_dwordx4 v[108:111], v[200:201], off
	v_lshl_add_u64 v[202:203], v[2:3], 0, v[28:29]
	global_load_dwordx4 v[112:115], v[202:203], off
	v_lshl_add_u64 v[204:205], v[2:3], 0, v[72:73]
	global_load_dwordx4 v[116:119], v[204:205], off
	global_load_dwordx4 v[120:123], v[74:75], off
	global_load_dwordx4 v[124:127], v[32:33], off offset:128
	v_lshl_add_u64 v[200:201], v[4:5], 0, v[30:31]
	global_load_dwordx4 v[128:131], v[200:201], off
	v_lshl_add_u64 v[202:203], v[4:5], 0, v[28:29]
	global_load_dwordx4 v[132:135], v[202:203], off
	v_lshl_add_u64 v[204:205], v[4:5], 0, v[72:73]
	global_load_dwordx4 v[136:139], v[204:205], off
	global_load_dwordx4 v[140:143], v[74:75], off offset:64
	global_load_dwordx4 v[144:147], v[32:33], off offset:192
	v_lshl_add_u64 v[200:201], v[6:7], 0, v[30:31]
	global_load_dwordx4 v[148:151], v[200:201], off
	v_lshl_add_u64 v[202:203], v[6:7], 0, v[28:29]
	global_load_dwordx4 v[152:155], v[202:203], off
	v_lshl_add_u64 v[204:205], v[6:7], 0, v[72:73]
	global_load_dwordx4 v[156:159], v[204:205], off
	global_load_dwordx4 v[160:163], v[66:67], off
	global_load_dwordx4 v[164:167], v[32:33], off offset:256
	v_lshl_add_u64 v[200:201], v[8:9], 0, v[30:31]
	global_load_dwordx4 v[168:171], v[200:201], off
	v_lshl_add_u64 v[202:203], v[8:9], 0, v[28:29]
	global_load_dwordx4 v[172:175], v[202:203], off
	v_lshl_add_u64 v[204:205], v[8:9], 0, v[72:73]
	global_load_dwordx4 v[176:179], v[204:205], off
	global_load_dwordx4 v[180:183], v[66:67], off offset:64
	global_load_dwordx4 v[184:187], v[32:33], off offset:320
	v_lshl_add_u64 v[200:201], v[10:11], 0, v[30:31]
	global_load_dwordx4 v[188:191], v[200:201], off
	v_lshl_add_u64 v[202:203], v[10:11], 0, v[28:29]
	global_load_dwordx4 v[192:195], v[202:203], off
	v_lshl_add_u64 v[204:205], v[10:11], 0, v[72:73]
	global_load_dwordx4 v[196:199], v[204:205], off
	s_waitcnt vmcnt(20)
	v_mfma_f32_16x16x32_bf16 v[52:55], v[80:83], v[84:87], 0
	v_mfma_f32_16x16x32_bf16 v[56:59], v[80:83], v[88:91], 0
	v_mfma_f32_16x16x32_bf16 v[60:63], v[80:83], v[92:95], 0
	v_mfma_f32_16x16x32_bf16 v[48:51], v[80:83], v[96:99], 0
	v_mfma_f32_16x16x32_bf16 v[52:55], v[100:103], v[104:107], v[52:55]
	v_mfma_f32_16x16x32_bf16 v[56:59], v[100:103], v[108:111], v[56:59]
	v_mfma_f32_16x16x32_bf16 v[60:63], v[100:103], v[112:115], v[60:63]
	v_mfma_f32_16x16x32_bf16 v[48:51], v[100:103], v[116:119], v[48:51]
	global_load_dwordx4 v[80:83], v[34:35], off
	global_load_dwordx4 v[84:87], v[32:33], off offset:384
	v_lshl_add_u64 v[200:201], v[12:13], 0, v[30:31]
	global_load_dwordx4 v[88:91], v[200:201], off
	v_lshl_add_u64 v[202:203], v[12:13], 0, v[28:29]
	global_load_dwordx4 v[92:95], v[202:203], off
	v_lshl_add_u64 v[204:205], v[12:13], 0, v[72:73]
	global_load_dwordx4 v[96:99], v[204:205], off
	global_load_dwordx4 v[100:103], v[34:35], off offset:64
	global_load_dwordx4 v[104:107], v[32:33], off offset:448
	v_lshl_add_u64 v[200:201], v[14:15], 0, v[30:31]
	global_load_dwordx4 v[108:111], v[200:201], off
	v_lshl_add_u64 v[202:203], v[14:15], 0, v[28:29]
	global_load_dwordx4 v[112:115], v[202:203], off
	v_lshl_add_u64 v[204:205], v[14:15], 0, v[72:73]
	global_load_dwordx4 v[116:119], v[204:205], off
	v_lshl_or_b32 v26, s40, 10, v37
	v_ashrrev_i32_e32 v27, 31, v26
	v_lshl_add_u64 v[26:27], v[26:27], 2, s[4:5]
	s_lshl_b64 s[4:5], s[38:39], 14
	s_waitcnt vmcnt(10)
	v_mfma_f32_16x16x32_bf16 v[52:55], v[120:123], v[124:127], v[52:55]
	v_mfma_f32_16x16x32_bf16 v[56:59], v[120:123], v[128:131], v[56:59]
	v_mfma_f32_16x16x32_bf16 v[60:63], v[120:123], v[132:135], v[60:63]
	v_mfma_f32_16x16x32_bf16 v[48:51], v[120:123], v[136:139], v[48:51]
	v_mfma_f32_16x16x32_bf16 v[52:55], v[140:143], v[144:147], v[52:55]
	v_mfma_f32_16x16x32_bf16 v[56:59], v[140:143], v[148:151], v[56:59]
	v_mfma_f32_16x16x32_bf16 v[60:63], v[140:143], v[152:155], v[60:63]
	v_mfma_f32_16x16x32_bf16 v[48:51], v[140:143], v[156:159], v[48:51]
	v_mfma_f32_16x16x32_bf16 v[52:55], v[160:163], v[164:167], v[52:55]
	v_mfma_f32_16x16x32_bf16 v[56:59], v[160:163], v[168:171], v[56:59]
	v_mfma_f32_16x16x32_bf16 v[60:63], v[160:163], v[172:175], v[60:63]
	v_mfma_f32_16x16x32_bf16 v[48:51], v[160:163], v[176:179], v[48:51]
	v_mfma_f32_16x16x32_bf16 v[52:55], v[180:183], v[184:187], v[52:55]
	v_mfma_f32_16x16x32_bf16 v[56:59], v[180:183], v[188:191], v[56:59]
	v_mfma_f32_16x16x32_bf16 v[60:63], v[180:183], v[192:195], v[60:63]
	v_mfma_f32_16x16x32_bf16 v[48:51], v[180:183], v[196:199], v[48:51]
	s_waitcnt vmcnt(0)
	v_mfma_f32_16x16x32_bf16 v[52:55], v[80:83], v[84:87], v[52:55]
	v_mfma_f32_16x16x32_bf16 v[56:59], v[80:83], v[88:91], v[56:59]
	v_mfma_f32_16x16x32_bf16 v[60:63], v[80:83], v[92:95], v[60:63]
	v_mfma_f32_16x16x32_bf16 v[48:51], v[80:83], v[96:99], v[48:51]
	v_mfma_f32_16x16x32_bf16 v[52:55], v[100:103], v[104:107], v[52:55]
	v_mfma_f32_16x16x32_bf16 v[56:59], v[100:103], v[108:111], v[56:59]
	v_mfma_f32_16x16x32_bf16 v[60:63], v[100:103], v[112:115], v[60:63]
	v_mfma_f32_16x16x32_bf16 v[48:51], v[100:103], v[116:119], v[48:51]
	s_nop 7
	s_nop 1
	ds_write2_b32 v45, v52, v56 offset1:16
	ds_write2_b32 v45, v53, v57 offset0:64 offset1:80
	ds_write2_b32 v45, v54, v58 offset0:128 offset1:144
	ds_write2_b32 v45, v55, v59 offset0:192 offset1:208
	ds_write2_b32 v45, v60, v48 offset0:32 offset1:48
	ds_write2_b32 v45, v61, v49 offset0:96 offset1:112
	ds_write2_b32 v45, v62, v50 offset0:160 offset1:176
	ds_write2_b32 v45, v63, v51 offset0:224 offset1:240
	s_waitcnt lgkmcnt(0)
	s_barrier
	global_load_dwordx2 v[80:81], v[26:27], off
	global_load_dwordx2 v[82:83], v[26:27], off offset:256
	global_load_dwordx2 v[84:85], v[26:27], off offset:512
	global_load_dwordx2 v[86:87], v[26:27], off offset:768
	global_load_dwordx2 v[88:89], v[26:27], off offset:1024
	global_load_dwordx2 v[90:91], v[26:27], off offset:1280
	global_load_dwordx2 v[92:93], v[26:27], off offset:1536
	global_load_dwordx2 v[94:95], v[26:27], off offset:1792
	global_load_dwordx2 v[96:97], v[26:27], off offset:2048
	global_load_dwordx2 v[98:99], v[26:27], off offset:2304
	global_load_dwordx2 v[100:101], v[26:27], off offset:2560
	global_load_dwordx2 v[102:103], v[26:27], off offset:2816
	global_load_dwordx2 v[104:105], v[26:27], off offset:3072
	global_load_dwordx2 v[106:107], v[26:27], off offset:3328
	global_load_dwordx2 v[108:109], v[26:27], off offset:3584
	global_load_dwordx2 v[110:111], v[26:27], off offset:3840
	s_waitcnt vmcnt(0)
	v_pk_add_f32 v[28:29], v[80:81], 0 op_sel_hi:[1,0]
	v_pk_add_f32 v[28:29], v[28:29], v[82:83]
	v_pk_add_f32 v[28:29], v[28:29], v[84:85]
	v_pk_add_f32 v[28:29], v[28:29], v[86:87]
	v_pk_add_f32 v[28:29], v[28:29], v[88:89]
	v_pk_add_f32 v[28:29], v[28:29], v[90:91]
	v_pk_add_f32 v[28:29], v[28:29], v[92:93]
	v_pk_add_f32 v[28:29], v[28:29], v[94:95]
	v_pk_add_f32 v[28:29], v[28:29], v[96:97]
	v_pk_add_f32 v[28:29], v[28:29], v[98:99]
	v_pk_add_f32 v[28:29], v[28:29], v[100:101]
	v_pk_add_f32 v[28:29], v[28:29], v[102:103]
	v_pk_add_f32 v[28:29], v[28:29], v[104:105]
	v_pk_add_f32 v[28:29], v[28:29], v[106:107]
	v_pk_add_f32 v[28:29], v[28:29], v[108:109]
	v_pk_add_f32 v[30:31], v[28:29], v[110:111]
	ds_read2st64_b64 v[26:29], v46 offset1:8
	s_waitcnt lgkmcnt(0)
	v_pk_add_f32 v[26:27], v[30:31], v[26:27]
	s_nop 0
	v_pk_add_f32 v[30:31], v[26:27], v[28:29]
	ds_read2st64_b64 v[26:29], v46 offset0:16 offset1:24
	s_waitcnt lgkmcnt(0)
	v_pk_add_f32 v[26:27], v[30:31], v[26:27]
	s_nop 0
	v_pk_add_f32 v[30:31], v[26:27], v[28:29]
	ds_read2st64_b64 v[26:29], v46 offset0:32 offset1:40
	s_waitcnt lgkmcnt(0)
	v_pk_add_f32 v[26:27], v[30:31], v[26:27]
	s_nop 0
	v_pk_add_f32 v[30:31], v[26:27], v[28:29]
	ds_read2st64_b64 v[26:29], v46 offset0:48 offset1:56
	s_waitcnt lgkmcnt(0)
	v_pk_add_f32 v[26:27], v[30:31], v[26:27]
	s_nop 0
	v_pk_add_f32 v[26:27], v[26:27], v[28:29]
	s_nop 0
	v_mul_f32_e32 v23, 0xbfb8aa3b, v26
	v_exp_f32_e32 v23, v23
	s_nop 0
	v_add_f32_e32 v23, 1.0, v23
	v_rcp_f32_e32 v28, v23
	v_mul_f32_e32 v23, 0xbfb8aa3b, v27
	v_exp_f32_e32 v23, v23
	s_nop 0
	v_add_f32_e32 v23, 1.0, v23
	v_rcp_f32_e32 v29, v23
	v_mov_b32_e32 v23, v44
	v_pk_mul_f32 v[26:27], v[26:27], v[28:29]
	v_mov_b32_e32 v28, 0
	ds_write_b64 v46, v[26:27] offset:32768
	v_lshl_add_u64 v[26:27], v[20:21], 0, s[4:5]
	s_mov_b64 s[4:5], 0
	v_mov_b32_e32 v29, v28
	s_waitcnt lgkmcnt(0)
	s_barrier
.LBB0_373:
	v_lshl_add_u64 v[34:35], v[26:27], 0, s[4:5]
	ds_read_b128 v[30:33], v23
	ds_read_b128 v[48:51], v23 offset:16
	ds_read_b128 v[52:55], v23 offset:32
	ds_read_b128 v[56:59], v23 offset:48
	global_load_dwordx2 v[80:81], v[34:35], off
	global_load_dwordx2 v[82:83], v[34:35], off offset:256
	global_load_dwordx2 v[84:85], v[34:35], off offset:512
	global_load_dwordx2 v[86:87], v[34:35], off offset:768
	global_load_dwordx2 v[88:89], v[34:35], off offset:1024
	global_load_dwordx2 v[90:91], v[34:35], off offset:1280
	global_load_dwordx2 v[92:93], v[34:35], off offset:1536
	global_load_dwordx2 v[94:95], v[34:35], off offset:1792
	global_load_dwordx2 v[96:97], v[34:35], off offset:2048
	global_load_dwordx2 v[98:99], v[34:35], off offset:2304
	global_load_dwordx2 v[100:101], v[34:35], off offset:2560
	global_load_dwordx2 v[102:103], v[34:35], off offset:2816
	global_load_dwordx2 v[104:105], v[34:35], off offset:3072
	global_load_dwordx2 v[106:107], v[34:35], off offset:3328
	global_load_dwordx2 v[108:109], v[34:35], off offset:3584
	global_load_dwordx2 v[110:111], v[34:35], off offset:3840
	s_add_u32 s4, s4, 0x1000
	s_addc_u32 s5, s5, 0
	v_add_u32_e32 v23, 64, v23
	s_cmpk_eq_i32 s4, 0x4000
	s_waitcnt vmcnt(0) lgkmcnt(0)
	v_pk_fma_f32 v[28:29], v[30:31], v[80:81], v[28:29] op_sel_hi:[0,1,1]
	v_pk_fma_f32 v[28:29], v[30:31], v[82:83], v[28:29] op_sel:[1,0,0]
	v_pk_fma_f32 v[28:29], v[32:33], v[84:85], v[28:29] op_sel_hi:[0,1,1]
	v_mov_b32_e32 v32, v33
	v_pk_fma_f32 v[28:29], v[32:33], v[86:87], v[28:29] op_sel_hi:[0,1,1]
	v_mov_b32_e32 v32, v51
	v_pk_fma_f32 v[28:29], v[48:49], v[88:89], v[28:29] op_sel_hi:[0,1,1]
	v_pk_fma_f32 v[28:29], v[48:49], v[90:91], v[28:29] op_sel:[1,0,0]
	v_pk_fma_f32 v[28:29], v[50:51], v[92:93], v[28:29] op_sel_hi:[0,1,1]
	v_pk_fma_f32 v[28:29], v[32:33], v[94:95], v[28:29] op_sel_hi:[0,1,1]
	v_mov_b32_e32 v32, v55
	v_pk_fma_f32 v[28:29], v[52:53], v[96:97], v[28:29] op_sel_hi:[0,1,1]
	v_pk_fma_f32 v[28:29], v[52:53], v[98:99], v[28:29] op_sel:[1,0,0]
	v_pk_fma_f32 v[28:29], v[54:55], v[100:101], v[28:29] op_sel_hi:[0,1,1]
	v_pk_fma_f32 v[28:29], v[32:33], v[102:103], v[28:29] op_sel_hi:[0,1,1]
	v_mov_b32_e32 v32, v59
	v_pk_fma_f32 v[28:29], v[56:57], v[104:105], v[28:29] op_sel_hi:[0,1,1]
	v_pk_fma_f32 v[28:29], v[56:57], v[106:107], v[28:29] op_sel:[1,0,0]
	v_pk_fma_f32 v[28:29], v[58:59], v[108:109], v[28:29] op_sel_hi:[0,1,1]
	v_pk_fma_f32 v[28:29], v[32:33], v[110:111], v[28:29] op_sel_hi:[0,1,1]
	s_cbranch_scc0 .LBB0_373
	v_add_u32_e32 v23, s8, v38
	s_movk_i32 s3, 0x7f8
	v_cmp_gt_i32_e64 s[40:41], s3, v23
	s_mov_b32 s3, 0x80808081
	s_cmpk_gt_u32 s7, 0x7f
	v_cndmask_b32_e64 v23, v221, v23, s[40:41]
	v_and_b32_e32 v25, 1, v23
	v_ashrrev_i32_e32 v23, 1, v23
	v_mul_hi_i32 v26, v23, s3
	v_add_u32_e32 v26, v26, v23
	v_lshrrev_b32_e32 v27, 31, v26
	v_ashrrev_i32_e32 v26, 7, v26
	v_add_u32_e32 v26, v26, v27
	s_movk_i32 s3, 0xff
	v_mul_lo_u32 v27, v26, s3
	v_sub_u32_e32 v23, v23, v27
	s_mov_b64 s[4:5], -1
	s_cbranch_scc0 .LBB0_378
	s_and_saveexec_b64 s[4:5], s[40:41]
	s_cbranch_execz .LBB0_377
	v_ashrrev_i32_e32 v27, 31, v26
	v_lshlrev_b64 v[30:31], 16, v[26:27]
	v_ashrrev_i32_e32 v32, 6, v23
	v_lshl_add_u64 v[30:31], s[90:91], 0, v[30:31]
	v_lshlrev_b32_e32 v64, 15, v25
	v_ashrrev_i32_e32 v33, 31, v32
	v_lshl_add_u64 v[30:31], v[30:31], 0, v[64:65]
	v_lshlrev_b64 v[32:33], 13, v[32:33]
	v_lshl_add_u64 v[30:31], v[30:31], 0, v[32:33]
	v_and_b32_e32 v64, 8, v23
	v_and_b32_e32 v27, 3, v23
	v_lshlrev_b32_e32 v33, 3, v23
	v_lshl_add_u64 v[30:31], v[30:31], 0, v[64:65]
	v_lshlrev_b32_e32 v64, 1, v27
	v_lshrrev_b32_e32 v27, 3, v23
	v_and_or_b32 v33, v33, 32, v40
	v_and_or_b32 v27, v27, 6, v39
	v_lshlrev_b32_e32 v33, 4, v33
	v_lshl_add_u64 v[30:31], v[30:31], 0, v[64:65]
	v_lshl_or_b32 v64, v27, 10, v33
	v_cvt_pk_bf16_f32 v32, v28, s0
	v_lshl_add_u64 v[30:31], v[30:31], 0, v[64:65]
	v_cvt_pk_bf16_f32 v27, v29, s0
	global_store_short v[30:31], v32, off
	global_store_short v[30:31], v27, off offset:16
